# attention l-sum as plain f32 adds placed in the QK-result wait slots (replacing s_nop), tail shortened
# speedup vs baseline: 1.0027x; 1.0027x over previous
; template <bool SHIFT> DEVI void attn_body(const Params& p, int l, int idx, unsigned char* smem, float lam, float lam_init) {
;     ...
;   for (int kt = kt0; kt < kt1; ++kt) {
;     const int buf = (kt - kt0) & 1;
;     const bool more = (kt + 1 < kt1);
;     if (more) AT_LOAD(kt + 1);
;     const unsigned char* kb = KB + buf * AT_KB;
;     const unsigned char* vb = VB + buf * AT_VB;
.LBB0_170:
	v_lshl_add_u64 v[178:179], v[178:179], 0, s[20:21]
	s_cmpk_lt_u32 s24, 0x83
	v_add_u32_e32 v240, 64, v240
	v_add_f32_e32 v180, v180, v92
	v_add_f32_e32 v181, v181, v93
	v_add_f32_e32 v180, v180, v90
	v_add_f32_e32 v181, v181, v91
	v_add_f32_e32 v180, v180, v66
	v_add_f32_e32 v181, v181, v67
	v_add_f32_e32 v180, v180, v64
	v_add_f32_e32 v181, v181, v65
	v_add_f32_e32 v180, v180, v94
	v_add_f32_e32 v181, v181, v95
	v_add_f32_e32 v180, v180, v72
	v_add_f32_e32 v181, v181, v73
	v_add_f32_e32 v180, v180, v68
	v_add_f32_e32 v181, v181, v69
	v_add_f32_e32 v180, v180, v70
	v_add_f32_e32 v181, v181, v71
	s_waitcnt lgkmcnt(0)
	s_barrier
	s_cbranch_scc0 .LBB0_175

; template <bool SHIFT> DEVI void attn_body(const Params& p, int l, int idx, unsigned char* smem, float lam, float lam_init) {
;     ...
;     const int buf = (kt - kt0) & 1;
;     const bool more = (kt + 1 < kt1);
;     if (more) AT_LOAD(kt + 1);
;     const unsigned char* kb = KB + buf * AT_KB;
;     const unsigned char* vb = VB + buf * AT_VB;
;     ...
;     {
;       f32x16 scA, scB;
;       AT_QK(0, 0, scA);
;       AT_QK(0, 1, scB);
;       AT_SPV(0, 0, scA);
;       AT_QK(1, 0, scA);
;       AT_SPV(0, 1, scB);
;       AT_QK(1, 1, scB);
;       AT_SPV(1, 0, scA);
;       AT_SPV(1, 1, scB);
.LBB0_173:
	s_add_i32 s24, s24, 1
	s_and_b32 s25, s24, 1
	v_lshl_or_b32 v216, s25, 13, v241
	v_add_u32_e32 v68, v216, v244
	ds_read_b128 v[64:67], v68
	v_add_u32_e32 v136, v216, v245
	ds_read_b128 v[132:135], v136
	s_mul_i32 s26, s25, 0x2200
	v_add_u32_e32 v128, s26, v242
	v_add_u32_e32 v137, 0x4000, v128
	v_add_u32_e32 v138, 0x5000, v128
	ds_read2_b64 v[128:131], v137 offset1:2
	ds_read2_b64 v[152:155], v138 offset0:32 offset1:34
	s_waitcnt lgkmcnt(3)
	v_mfma_f32_32x32x16_bf16 v[80:95], v[64:67], v[96:99], 0
	ds_read2_b64 v[144:147], v137 offset0:4 offset1:6
	ds_read2_b64 v[156:159], v138 offset0:36 offset1:38
	ds_read_b128 v[64:67], v68 offset:4096
	ds_read2_b64 v[140:143], v137 offset0:8 offset1:10
	ds_read2_b64 v[148:151], v138 offset0:40 offset1:42
	v_add_u32_e32 v217, v216, v246
	v_add_u32_e32 v220, v216, v247
	s_waitcnt lgkmcnt(7)
	v_mfma_f32_32x32x16_bf16 v[80:95], v[132:135], v[100:103], v[80:95]
	ds_read2_b64 v[132:135], v137 offset0:12 offset1:14
	s_andn2_b64 vcc, exec, s[22:23]
	s_nop 9
	v_exp_f32_e32 v192, v80
	v_exp_f32_e32 v193, v81
	v_exp_f32_e32 v188, v82
	v_exp_f32_e32 v189, v83
	v_exp_f32_e32 v186, v84
	v_exp_f32_e32 v187, v85
	v_exp_f32_e32 v184, v86
	v_exp_f32_e32 v185, v87
	v_cvt_pk_bf16_f32 v80, v192, v193
	v_cvt_pk_bf16_f32 v81, v188, v189
	v_cvt_pk_bf16_f32 v82, v186, v187
	v_cvt_pk_bf16_f32 v83, v184, v185
	v_exp_f32_e32 v198, v88
	s_waitcnt lgkmcnt(7)
	v_mfma_f32_32x32x16_bf16 v[48:63], v[128:131], v[80:83], v[48:63]
	v_exp_f32_e32 v199, v89
	v_exp_f32_e32 v196, v90
	v_exp_f32_e32 v197, v91
	v_exp_f32_e32 v190, v92
	v_exp_f32_e32 v191, v93
	v_exp_f32_e32 v194, v94
	v_exp_f32_e32 v195, v95
	s_waitcnt lgkmcnt(6)
	v_mfma_f32_32x32x16_bf16 v[16:31], v[152:155], v[80:83], v[16:31]
	v_cvt_pk_bf16_f32 v80, v198, v199
	v_cvt_pk_bf16_f32 v81, v196, v197
	v_cvt_pk_bf16_f32 v82, v190, v191
	v_cvt_pk_bf16_f32 v83, v194, v195
	s_waitcnt lgkmcnt(5)
	v_mfma_f32_32x32x16_bf16 v[48:63], v[144:147], v[80:83], v[48:63]
	s_waitcnt lgkmcnt(4)
	v_mfma_f32_32x32x16_bf16 v[16:31], v[156:159], v[80:83], v[16:31]
	ds_read_b128 v[80:83], v136 offset:4096
	ds_read2_b64 v[136:139], v138 offset0:44 offset1:46
	s_waitcnt lgkmcnt(5)
	v_mfma_f32_32x32x16_bf16 v[64:79], v[64:67], v[96:99], 0
	s_waitcnt lgkmcnt(1)
	v_mfma_f32_32x32x16_bf16 v[64:79], v[80:83], v[100:103], v[64:79]
	ds_read_b128 v[80:83], v217
	v_add_f32_e32 v182, v182, v192
	v_add_f32_e32 v183, v183, v193
	v_add_f32_e32 v182, v182, v188
	v_add_f32_e32 v183, v183, v189
	v_add_f32_e32 v182, v182, v186
	v_add_f32_e32 v183, v183, v187
	v_add_f32_e32 v182, v182, v184
	v_add_f32_e32 v183, v183, v185
	v_add_f32_e32 v182, v182, v198
	v_add_f32_e32 v183, v183, v199
	v_add_f32_e32 v182, v182, v196
	v_add_f32_e32 v183, v183, v197
	v_add_f32_e32 v182, v182, v190
	v_add_f32_e32 v183, v183, v191
	v_add_f32_e32 v182, v182, v194
	v_add_f32_e32 v183, v183, v195
	v_exp_f32_e32 v204, v64
	v_exp_f32_e32 v205, v65
	v_exp_f32_e32 v202, v66
	v_exp_f32_e32 v203, v67
	v_exp_f32_e32 v200, v68
	v_exp_f32_e32 v201, v69
	v_exp_f32_e32 v206, v70
	v_exp_f32_e32 v207, v71
	v_cvt_pk_bf16_f32 v64, v204, v205
	v_cvt_pk_bf16_f32 v65, v202, v203
	v_cvt_pk_bf16_f32 v66, v200, v201
	v_cvt_pk_bf16_f32 v67, v206, v207
	v_exp_f32_e32 v214, v72
	v_mfma_f32_32x32x16_bf16 v[48:63], v[140:143], v[64:67], v[48:63]
	v_exp_f32_e32 v215, v73
	v_exp_f32_e32 v212, v74
	v_exp_f32_e32 v213, v75
	v_exp_f32_e32 v208, v76
	v_exp_f32_e32 v209, v77
	v_exp_f32_e32 v210, v78
	v_exp_f32_e32 v211, v79
	v_mfma_f32_32x32x16_bf16 v[16:31], v[148:151], v[64:67], v[16:31]
	v_cvt_pk_bf16_f32 v64, v214, v215
	v_cvt_pk_bf16_f32 v65, v212, v213
	v_cvt_pk_bf16_f32 v66, v208, v209
	v_cvt_pk_bf16_f32 v67, v210, v211
	s_nop 0
	v_mfma_f32_32x32x16_bf16 v[48:63], v[132:135], v[64:67], v[48:63]
	s_waitcnt lgkmcnt(1)
	v_mfma_f32_32x32x16_bf16 v[16:31], v[136:139], v[64:67], v[16:31]
	ds_read_b128 v[64:67], v220
	s_waitcnt lgkmcnt(1)
; template <bool SHIFT> DEVI void attn_body(const Params& p, int l, int idx, unsigned char* smem, float lam, float lam_init) {
;     ...
;     {
;       f32x16 scA, scB;
;       AT_QK(0, 0, scA);
;       AT_QK(0, 1, scB);
;       AT_SPV(0, 0, scA);
;       AT_QK(1, 0, scA);
;       AT_SPV(0, 1, scB);
;       AT_QK(1, 1, scB);
;       AT_SPV(1, 0, scA);
;       AT_SPV(1, 1, scB);
;     }
;     ...
;     if (more) AT_STORE(buf ^ 1);
;     __syncthreads();
;   }
	v_mfma_f32_32x32x16_bf16 v[80:95], v[80:83], v[104:107], 0
	s_waitcnt lgkmcnt(0)
	v_mfma_f32_32x32x16_bf16 v[80:95], v[64:67], v[108:111], v[80:95]
	ds_read_b128 v[64:67], v217 offset:4096
	s_waitcnt lgkmcnt(0)
	v_mfma_f32_32x32x16_bf16 v[64:79], v[64:67], v[104:107], 0
	v_add_f32_e32 v182, v182, v204
	v_add_f32_e32 v183, v183, v205
	v_add_f32_e32 v182, v182, v202
	v_add_f32_e32 v183, v183, v203
	v_add_f32_e32 v182, v182, v200
	v_add_f32_e32 v183, v183, v201
	v_add_f32_e32 v182, v182, v206
	v_add_f32_e32 v183, v183, v207
	v_add_f32_e32 v182, v182, v214
	v_add_f32_e32 v183, v183, v215
	v_add_f32_e32 v182, v182, v212
	v_add_f32_e32 v183, v183, v213
	v_add_f32_e32 v182, v182, v208
	v_add_f32_e32 v183, v183, v209
	v_add_f32_e32 v182, v182, v210
	v_add_f32_e32 v183, v183, v211
	v_exp_f32_e32 v218, v80
	v_exp_f32_e32 v219, v81
	v_exp_f32_e32 v216, v82
	v_exp_f32_e32 v217, v83
	v_exp_f32_e32 v82, v84
	v_exp_f32_e32 v83, v85
	v_exp_f32_e32 v80, v86
	v_exp_f32_e32 v81, v87
	v_cvt_pk_bf16_f32 v230, v218, v219
	v_cvt_pk_bf16_f32 v231, v216, v217
	v_cvt_pk_bf16_f32 v232, v82, v83
	v_cvt_pk_bf16_f32 v233, v80, v81
	v_exp_f32_e32 v86, v92
	v_mfma_f32_32x32x16_bf16 v[32:47], v[128:131], v[230:233], v[32:47]
	v_exp_f32_e32 v128, v88
	v_exp_f32_e32 v129, v89
	v_exp_f32_e32 v88, v90
	v_exp_f32_e32 v89, v91
	v_exp_f32_e32 v87, v93
	v_exp_f32_e32 v84, v94
	v_exp_f32_e32 v85, v95
	v_mfma_f32_32x32x16_bf16 v[0:15], v[152:155], v[230:233], v[0:15]
	v_cvt_pk_bf16_f32 v90, v128, v129
	v_cvt_pk_bf16_f32 v91, v88, v89
	v_cvt_pk_bf16_f32 v92, v86, v87
	v_cvt_pk_bf16_f32 v93, v84, v85
	s_nop 0
	v_mfma_f32_32x32x16_bf16 v[32:47], v[144:147], v[90:93], v[32:47]
	v_mfma_f32_32x32x16_bf16 v[0:15], v[156:159], v[90:93], v[0:15]
	ds_read_b128 v[90:93], v220 offset:4096
	s_waitcnt lgkmcnt(0)
	v_mfma_f32_32x32x16_bf16 v[64:79], v[90:93], v[108:111], v[64:79]
	v_add_f32_e32 v180, v180, v218
	v_add_f32_e32 v181, v181, v219
	v_add_f32_e32 v180, v180, v216
	v_add_f32_e32 v181, v181, v217
	v_add_f32_e32 v180, v180, v82
	v_add_f32_e32 v181, v181, v83
	v_add_f32_e32 v180, v180, v80
	v_add_f32_e32 v181, v181, v81
	v_add_f32_e32 v180, v180, v128
	v_add_f32_e32 v181, v181, v129
	v_add_f32_e32 v180, v180, v88
	v_add_f32_e32 v181, v181, v89
	v_add_f32_e32 v180, v180, v86
	v_add_f32_e32 v181, v181, v87
	v_add_f32_e32 v180, v180, v84
	v_add_f32_e32 v181, v181, v85
	v_exp_f32_e32 v92, v64
	v_exp_f32_e32 v93, v65
	v_exp_f32_e32 v90, v66
	v_exp_f32_e32 v91, v67
	v_exp_f32_e32 v66, v68
	v_exp_f32_e32 v67, v69
	v_exp_f32_e32 v64, v70
	v_exp_f32_e32 v65, v71
	v_cvt_pk_bf16_f32 v144, v92, v93
	v_cvt_pk_bf16_f32 v145, v90, v91
	v_cvt_pk_bf16_f32 v146, v66, v67
	v_cvt_pk_bf16_f32 v147, v64, v65
	v_exp_f32_e32 v94, v72
	v_mfma_f32_32x32x16_bf16 v[32:47], v[140:143], v[144:147], v[32:47]
	v_exp_f32_e32 v95, v73
	v_exp_f32_e32 v72, v74
	v_exp_f32_e32 v73, v75
	v_exp_f32_e32 v68, v76
	v_exp_f32_e32 v69, v77
	v_exp_f32_e32 v70, v78
	v_exp_f32_e32 v71, v79
	v_mfma_f32_32x32x16_bf16 v[0:15], v[148:151], v[144:147], v[0:15]
	v_cvt_pk_bf16_f32 v74, v94, v95
	v_cvt_pk_bf16_f32 v75, v72, v73
	v_cvt_pk_bf16_f32 v76, v68, v69
	v_cvt_pk_bf16_f32 v77, v70, v71
	s_nop 0
	v_mfma_f32_32x32x16_bf16 v[32:47], v[132:135], v[74:77], v[32:47]
	v_mfma_f32_32x32x16_bf16 v[0:15], v[136:139], v[74:77], v[0:15]
	s_cbranch_vccnz .LBB0_170
	s_xor_b32 s22, s25, 1
	v_lshl_add_u32 v74, s22, 13, v173
	v_add_u32_e32 v75, v74, v243
	v_add_u32_e32 v74, v74, v248
	s_mulk_i32 s22, 0x2200
	s_waitcnt vmcnt(3)
	ds_write_b128 v74, v[112:115]
	v_add_u32_e32 v74, s22, v249
	s_waitcnt vmcnt(2)
	ds_write_b128 v75, v[116:119]
	v_add_u32_e32 v75, 0x4000, v74
	v_add_u32_e32 v74, 0x4010, v74
	s_waitcnt vmcnt(0)
	ds_write2_b64 v75, v[120:121], v[122:123] offset1:1
	ds_write2_b64 v74, v[124:125], v[126:127] offset1:1
	s_branch .LBB0_170
